# mixer B: next item's Q fragments DMA'd into LDS during the epilogue (item index requested at epilogue start)
# baseline (speedup 1.0000x reference)
; #define LAS __attribute__((address_space(3)))
; __global__ void __launch_bounds__(NTHREADS) hybrid_fwd(Params p) {
;     extern __shared__ __attribute__((aligned(16))) unsigned char lds_raw[];
;     LAS unsigned char* lds = (LAS unsigned char*)lds_raw;
;     cg::grid_group grid = cg::this_grid();
;     bf16_t* hb = (bf16_t*)(p.ws + WS_HB);
;     bf16_t* z = (bf16_t*)(p.ws + WS_Z);
;     unsigned* barw = (unsigned*)(p.ws + WS_BAR);
;     volatile LAS unsigned* bst = (volatile LAS unsigned*)(lds + LDS_MAIN);
;     {
;         const int tid = threadIdx.x, lane = tid & 63, wave = __builtin_amdgcn_readfirstlane(tid >> 6);
;         const int G = gridDim.x, gw = blockIdx.x * NWAVES + wave, NGW = G * NWAVES;
;         if (tid < 2) bst[tid] = 0u;
;         if (blockIdx.x == 0) { for (int i = tid; i < XCD_BAR_WORDS; i += NTHREADS) barw[i] = 0u; for (int i = tid; i < 4 * 8 * 64; i += NTHREADS) ((unsigned*)(p.ws + WS_Q))[i] = 0u; }
_Z10hybrid_fwd6Params:
	s_mov_b32 s101, 0
	s_mov_b32 s100, 0
	s_load_dwordx8 s[88:95], s[0:1], 0x40
	s_load_dword s99, s[0:1], 0x68
	s_add_u32 s6, s0, 0x68
	v_and_b32_e32 v34, 0x3ff, v0
	s_addc_u32 s7, s1, 0
	v_readfirstlane_b32 s16, v34
	v_cmp_gt_u32_e32 vcc, 2, v34
	s_and_saveexec_b64 s[8:9], vcc
	v_lshl_add_u32 v1, v34, 2, 0
	v_add_u32_e32 v1, 0x24000, v1
	v_mov_b32_e32 v2, 0
	ds_write_b32 v1, v2
	s_or_b64 exec, exec, s[8:9]
	s_waitcnt lgkmcnt(0)
	s_add_u32 s96, s94, 0x1c900000
	s_addc_u32 s97, s95, 0
	s_cmp_lg_u32 s2, 0
	s_mov_b32 s8, 0
	s_cbranch_scc1 .LBB0_14
	v_sub_u32_e32 v1, 0xd7f, v34
	v_lshrrev_b32_e32 v4, 9, v1
	v_add_u32_e32 v1, 2, v4
	v_add_u32_e32 v3, 0x200, v34
	v_mov_b32_e32 v2, v34
	v_and_b32_e32 v10, 14, v1
	v_mov_b32_e32 v5, v4
	v_mov_b32_e32 v1, v34
	s_mov_b64 s[10:11], 0
	s_mov_b32 s9, 1
	v_mov_b32_e32 v7, 0
	s_mov_b32 s12, s8
	v_mov_b64_e32 v[8:9], v[2:3]
	s_branch .LBB0_5

; DI int lane_id_fresh() { unsigned zero; asm volatile("v_mov_b32 %0, 0" : "=v"(zero)); return (int)__builtin_amdgcn_mbcnt_hi(~0u, __builtin_amdgcn_mbcnt_lo(~0u, zero)); }
; __global__ void __launch_bounds__(NTHREADS) hybrid_fwd(Params p) {
;     ...
;             while (attn_next(aq, lane_id_fresh() == 0, qs, hd)) attnB_item(z, hd, qs == NQS ? -1 : qs, vs, lane_id_fresh());
.LBB0_131:
	s_and_b64 vcc, exec, s[0:1]
	s_cbranch_vccnz .LBB0_159
	s_bitcmp1_b32 s101, 31
	s_cbranch_scc0 .LBB0_132
	s_and_b32 s24, s101, 0x3ff
	s_bfe_u32 s23, s101, 0x4000c
	s_branch .Litem_B

; DI int lane_id_fresh() { unsigned zero; asm volatile("v_mov_b32 %0, 0" : "=v"(zero)); return (int)__builtin_amdgcn_mbcnt_hi(~0u, __builtin_amdgcn_mbcnt_lo(~0u, zero)); }
; DI void attnB_item(bf16_t* z, int hh, int qs, LAS bf16_t* vs, int lane) {
;     const int c = lane & 31, h = lane >> 5;
;     const bool metaq = qs < 0;
;     const int qrow = metaq ? SEQ + c : 32 * qs + c;
;     const int qpos = metaq ? (c < NMETA ? c : 0) : NMETA + 32 * qs + c;
;     const int trb = (4 * h + ((lane & 15) >> 2)) * PB + 16 * ((lane >> 4) & 1) + 4 * (lane & 3);
;     const int qrow0 = metaq ? SEQ : 32 * qs;
; __global__ void __launch_bounds__(NTHREADS) hybrid_fwd(Params p) {
;     ...
;             while (attn_next(aq, lane_id_fresh() == 0, qs, hd)) attnB_item(z, hd, qs == NQS ? -1 : qs, vs, lane_id_fresh());
.Litem_B:
	s_cmpk_lg_i32 s24, 0x200
	v_mov_b32 v0, 0
	s_cselect_b32 s6, s24, -1
	v_mbcnt_lo_u32_b32 v0, -1, v0
	v_mbcnt_hi_u32_b32 v2, -1, v0
	s_cmp_gt_i32 s6, -1
	v_and_b32_e32 v178, 31, v2
	s_cselect_b64 s[0:1], -1, 0
	s_mov_b64 s[4:5], -1
	s_and_b64 vcc, exec, s[0:1]
	v_cmp_gt_u32_e64 s[36:37], 16, v178
	s_cbranch_vccnz .LBB0_147
	s_nop 0
	v_cndmask_b32_e64 v179, 0, v178, s[36:37]
	s_mov_b64 s[4:5], 0

; #define LAS __attribute__((address_space(3)))
; DI size_t zrowU(int row0, int NT) { return ((size_t)((row0 >> 8) * NT) << 16) + (size_t)((((row0 >> 7) & 1) << 15) | (((row0 >> 5) & 1) << 14) | (((row0 >> 6) & 1) << 11)); }
; DI unsigned zlaneRC(int r5, int col) { return (unsigned)(((col >> 8) << 16) | ((r5 >> 4) << 13) | (((col >> 7) & 1) << 12) | (((col >> 5) & 3) << 9) | (((col >> 3) & 3) << 7) | ((r5 & 15) << 3) | (col & 7)); }
; DI void attnB_item(bf16_t* z, int hh, int qs, LAS bf16_t* vs, int lane) {
;     ...
;     LAS bf16x8* qs_lds = (LAS bf16x8*)(vs + 32 * PB) + lane;
;     { const bf16_t* qp = z + zrowU(qrow0, 32) + zlaneRC(c, hh * 128 + 8 * h);
;       bf16x8 qf[8];
; #pragma unroll
;       for (int s = 0; s < 8; ++s) qf[s] = *(const bf16x8*)(qp + (((s >> 1) << 9) | ((s & 1) << 8)));
;       asm volatile("s_waitcnt lgkmcnt(0)" ::: "memory");
; #pragma unroll
;       for (int s = 0; s < 8; ++s) qs_lds[64 * s] = qf[s]; }
;     f32x16 acc[4];
; #pragma unroll
;     for (int dt = 0; dt < 4; ++dt)
; #pragma unroll
;         for (int i = 0; i < 16; ++i) acc[dt][i] = 0.f;
;     float later = 0.f;
;     int t = metaq ? -1 : qs;
;     const int tfirst = t;
;     const bf16_t* kbase = z + zlaneRC(c, 2048 + hh * 128 + 8 * h);
;     const bf16_t* vbase = z + zlaneRC(lane & 15, 4096 + hh * 128 + 8 * (lane >> 4));
;     bf16x8 kf[8]; u32x4 vv[8];
;     { const size_t ro = zrowU(t < 0 ? SEQ : 32 * t, 32);
; #pragma unroll
;       for (int s = 0; s < 8; ++s) kf[s] = *(const bf16x8*)(kbase + ro + (((s >> 1) << 9) | ((s & 1) << 8)));
; #pragma unroll
;       for (int i = 0; i < 8; ++i) vv[i] = *(const u32x4*)(vbase + ro + (((i >> 2) << 13) | ((i & 3) << 9))); }
.LBB0_149:
	s_lshr_b32 s5, s4, 3
	s_and_b32 s78, s5, 0x1fffffe0
	s_lshl_b32 s5, s4, 8
	s_lshl_b32 s7, s4, 9
	s_and_b32 s5, s5, 0x8000
	s_and_b32 s7, s7, 0x4000
	s_lshl_b32 s4, s4, 5
	s_or_b32 s5, s5, s7
	s_and_b32 s4, s4, 0x800
	s_or_b32 s7, s5, s4
	s_lshl_b64 s[4:5], s[78:79], 17
	s_add_u32 s4, s82, s4
	s_addc_u32 s5, s83, s5
	s_lshl_b32 s7, s7, 1
	s_add_u32 s46, s4, s7
	v_ashrrev_i32_e32 v180, 5, v2
	s_addc_u32 s47, s5, 0
	s_lshl_b32 s27, s23, 7
	v_lshl_add_u32 v0, v180, 3, s27
	v_lshlrev_b32_e32 v3, 8, v0
	v_lshlrev_b32_e32 v0, 5, v0
	v_and_b32_e32 v36, 0x1000, v0
	v_lshlrev_b32_e32 v0, 7, v180
	v_lshlrev_b32_e32 v4, 9, v178
	v_and_b32_e32 v37, 0x780, v0
	v_lshlrev_b32_e32 v0, 3, v178
	s_movk_i32 s4, 0x2078
	v_bitop3_b32 v181, v0, s4, v4 bitop3:0xc8
	v_and_b32_e32 v3, 0xffff0000, v3
	v_or_b32_e32 v0, v181, v37
	v_or3_b32 v0, v0, v36, v3
	v_lshl_add_u64 v[32:33], v[0:1], 1, s[46:47]
	s_bitcmp1_b32 s101, 31
	s_cbranch_scc1 .Lpq_skipQ_B
	global_load_dwordx4 v[4:7], v[32:33], off
	global_load_dwordx4 v[8:11], v[32:33], off offset:512
	global_load_dwordx4 v[12:15], v[32:33], off offset:1024
	global_load_dwordx4 v[16:19], v[32:33], off offset:1536
	global_load_dwordx4 v[20:23], v[32:33], off offset:2048
	global_load_dwordx4 v[24:27], v[32:33], off offset:2560
	global_load_dwordx4 v[28:31], v[32:33], off offset:3072
	s_nop 0
	global_load_dwordx4 v[32:35], v[32:33], off offset:3584
.Lpq_skipQ_B:
	v_ashrrev_i32_e32 v41, 1, v2
	s_max_i32 s28, s6, -1
	v_bfe_u32 v0, v2, 2, 2
	v_lshlrev_b32_e32 v183, 2, v180
	v_and_b32_e32 v42, -8, v41
	s_add_i32 s4, s27, 0x1000
	s_lshl_b32 s6, s28, 5
	v_or_b32_e32 v44, v183, v0
	v_add_u32_e32 v0, s4, v42
	s_and_b64 s[4:5], exec, s[0:1]
	s_cselect_b32 s4, s6, 0x4000
	s_lshl_b32 s6, s4, 8
	s_lshl_b32 s7, s4, 9
	s_ashr_i32 s5, s4, 3
	s_lshl_b32 s8, s4, 5
	s_and_b32 s6, s6, 0x8000
	s_and_b32 s7, s7, 0x4000
	v_and_b32_e32 v38, 15, v2
	v_lshlrev_b32_e32 v45, 8, v0
	v_lshlrev_b32_e32 v0, 5, v0
	v_or_b32_e32 v3, v3, v36
	s_and_b32 s4, s5, 0xffffffe0
	s_and_b32 s8, s8, 0x800
	s_or_b32 s6, s6, s7
	v_lshlrev_b32_e32 v41, 4, v41
	v_lshlrev_b32_e32 v43, 3, v38
	v_and_b32_e32 v36, 0x1000, v0
	v_or3_b32 v0, v3, v37, v181
	s_ashr_i32 s5, s4, 31
	s_or_b32 s6, s6, s8
	v_and_b32_e32 v41, 0x780, v41
	v_and_or_b32 v43, v45, s12, v43
	v_add_u32_e32 v0, 0x80000, v0
	s_lshl_b64 s[4:5], s[4:5], 17
	s_lshl_b32 s6, s6, 1
	v_lshl_add_u64 v[158:159], v[0:1], 1, s[82:83]
	v_or3_b32 v0, v43, v36, v41
	s_or_b32 s4, s4, s6
	v_lshl_add_u32 v182, v2, 4, s25
	s_waitcnt lgkmcnt(0)
	v_lshl_add_u64 v[36:37], v[158:159], 0, s[4:5]
	v_lshl_add_u64 v[160:161], v[0:1], 1, s[82:83]
	global_load_dwordx4 v[114:117], v[36:37], off
	global_load_dwordx4 v[118:121], v[36:37], off offset:512
	global_load_dwordx4 v[122:125], v[36:37], off offset:1024
	global_load_dwordx4 v[126:129], v[36:37], off offset:1536
	v_and_b32_e32 v40, 16, v2
	v_lshlrev_b32_e32 v3, 3, v2
	v_lshlrev_b32_e32 v0, 1, v40
	v_and_b32_e32 v3, 24, v3
	v_lshlrev_b32_e32 v39, 2, v2
	v_add3_u32 v3, s25, v0, v3
	v_cmp_gt_u32_e64 s[36:37], 32, v2
	v_mov_b32_e32 v189, 0
	v_xor_b32_e32 v184, 0x80, v39
	v_or_b32_e32 v185, 1, v183
	v_or_b32_e32 v186, 2, v183
	v_or_b32_e32 v187, 3, v183
	v_add_u32_e32 v163, 10, v183
	v_add_u32_e32 v0, 8, v183
	v_add_u32_e32 v165, 11, v183
	v_add_u32_e32 v162, 9, v183
	v_add_u32_e32 v167, 18, v183
	v_add_u32_e32 v164, 16, v183
	v_add_u32_e32 v169, 19, v183
	v_add_u32_e32 v166, 17, v183
	v_add_u32_e32 v171, 26, v183
	s_bitcmp1_b32 s101, 31
	s_cbranch_scc1 .Lpq_skipL_B
	s_waitcnt vmcnt(11)
	ds_write_b128 v182, v[4:7] offset:10240
	s_waitcnt vmcnt(10)
	ds_write_b128 v182, v[8:11] offset:11264
	s_waitcnt vmcnt(9)
	ds_write_b128 v182, v[12:15] offset:12288
	s_waitcnt vmcnt(8)
	ds_write_b128 v182, v[16:19] offset:13312
	s_waitcnt vmcnt(7)
	ds_write_b128 v182, v[20:23] offset:14336
	s_waitcnt vmcnt(6)
	ds_write_b128 v182, v[24:27] offset:15360
	s_waitcnt vmcnt(5)
	ds_write_b128 v182, v[28:31] offset:16384
	s_waitcnt vmcnt(4)
	ds_write_b128 v182, v[32:35] offset:17408
.Lpq_skipL_B:
	s_mov_b32 s101, 0
	v_lshl_add_u64 v[4:5], v[160:161], 0, s[4:5]
	global_load_dwordx4 v[130:133], v[36:37], off offset:2048
	global_load_dwordx4 v[134:137], v[36:37], off offset:2560
	global_load_dwordx4 v[138:141], v[36:37], off offset:3072
	global_load_dwordx4 v[142:145], v[36:37], off offset:3584
	global_load_dwordx4 v[82:85], v[4:5], off
	global_load_dwordx4 v[86:89], v[4:5], off offset:1024
	global_load_dwordx4 v[90:93], v[4:5], off offset:2048
	global_load_dwordx4 v[94:97], v[4:5], off offset:3072
	v_add_co_u32_e32 v4, vcc, s3, v4
	s_movk_i32 s4, 0x140
	s_nop 0
	v_addc_co_u32_e32 v5, vcc, 0, v5, vcc
	global_load_dwordx4 v[98:101], v[4:5], off
	global_load_dwordx4 v[102:105], v[4:5], off offset:1024
	global_load_dwordx4 v[106:109], v[4:5], off offset:2048
	global_load_dwordx4 v[110:113], v[4:5], off offset:3072
	v_mul_lo_u32 v2, v44, s4
	v_mul_u32_u24_e32 v4, 0x140, v38
	v_lshlrev_b32_e32 v5, 1, v42
	v_add_u32_e32 v168, 24, v183
	v_add_u32_e32 v173, 27, v183
	v_add_u32_e32 v170, 25, v183
	v_add3_u32 v188, s25, v4, v5
	v_add_u32_e32 v190, v3, v2
	s_mov_b32 s30, s28
	v_mov_b32_e32 v50, 0
	v_mov_b32_e32 v51, v189
	v_mov_b32_e32 v52, v189
	v_mov_b32_e32 v53, v189
	v_mov_b32_e32 v54, v189
	v_mov_b32_e32 v55, v189
	v_mov_b32_e32 v56, v189
	v_mov_b32_e32 v57, v189
	v_mov_b32_e32 v58, v189
	v_mov_b32_e32 v59, v189
	v_mov_b32_e32 v60, v189
	v_mov_b32_e32 v61, v189
	v_mov_b32_e32 v62, v189
	v_mov_b32_e32 v63, v189
	v_mov_b32_e32 v64, v189
	v_mov_b32_e32 v65, v189
	v_mov_b32_e32 v34, 0
	v_mov_b32_e32 v35, v189
	v_mov_b32_e32 v36, v189
	v_mov_b32_e32 v37, v189
	v_mov_b32_e32 v38, v189
	v_mov_b32_e32 v39, v189
	v_mov_b32_e32 v40, v189
	v_mov_b32_e32 v41, v189
	v_mov_b32_e32 v42, v189
	v_mov_b32_e32 v43, v189
	v_mov_b32_e32 v44, v189
	v_mov_b32_e32 v45, v189
	v_mov_b32_e32 v46, v189
	v_mov_b32_e32 v47, v189
	v_mov_b32_e32 v48, v189
	v_mov_b32_e32 v49, v189
	v_mov_b32_e32 v18, 0
	v_mov_b32_e32 v19, v189
	v_mov_b32_e32 v20, v189
	v_mov_b32_e32 v21, v189
	v_mov_b32_e32 v22, v189
	v_mov_b32_e32 v23, v189
	v_mov_b32_e32 v24, v189
	v_mov_b32_e32 v25, v189
	v_mov_b32_e32 v26, v189
	v_mov_b32_e32 v27, v189
	v_mov_b32_e32 v28, v189
	v_mov_b32_e32 v29, v189
	v_mov_b32_e32 v30, v189
	v_mov_b32_e32 v31, v189
	v_mov_b32_e32 v32, v189
	v_mov_b32_e32 v33, v189
	v_mov_b32_e32 v2, 0
	v_mov_b32_e32 v3, v189
	v_mov_b32_e32 v4, v189
	v_mov_b32_e32 v5, v189
	v_mov_b32_e32 v6, v189
	v_mov_b32_e32 v7, v189
	v_mov_b32_e32 v8, v189
	v_mov_b32_e32 v9, v189
	v_mov_b32_e32 v10, v189
	v_mov_b32_e32 v11, v189
	v_mov_b32_e32 v12, v189
	v_mov_b32_e32 v13, v189
	v_mov_b32_e32 v14, v189
	v_mov_b32_e32 v15, v189
	v_mov_b32_e32 v16, v189
	v_mov_b32_e32 v17, v189
	s_branch .LBB0_151

; #define LAS __attribute__((address_space(3)))
; DI unsigned pk2(float a, float b) { f32x2 v = {a, b}; bf16v2 r = __builtin_convertvector(v, bf16v2); return __builtin_bit_cast(unsigned, r); }
; DI float bf_lo(unsigned u) { return __uint_as_float(u << 16); }
; DI float bf_hi(unsigned u) { return __uint_as_float(u & 0xffff0000u); }
; DI size_t zrowU(int row0, int NT) { return ((size_t)((row0 >> 8) * NT) << 16) + (size_t)((((row0 >> 7) & 1) << 15) | (((row0 >> 5) & 1) << 14) | (((row0 >> 6) & 1) << 11)); }
; DI void attnB_item(bf16_t* z, int hh, int qs, LAS bf16_t* vs, int lane) {
;     ...
;     LAS bf16x8* qs_lds = (LAS bf16x8*)(vs + 32 * PB) + lane;
;     { const bf16_t* qp = z + zrowU(qrow0, 32) + zlaneRC(c, hh * 128 + 8 * h);
;       bf16x8 qf[8];
; #pragma unroll
;       for (int s = 0; s < 8; ++s) qf[s] = *(const bf16x8*)(qp + (((s >> 1) << 9) | ((s & 1) << 8)));
;       asm volatile("s_waitcnt lgkmcnt(0)" ::: "memory");
; #pragma unroll
;       for (int s = 0; s < 8; ++s) qs_lds[64 * s] = qf[s]; }
;     ...
;     if (!metaq || c < NMETA) {
;         bf16_t* orow = z + zrowU(qrow0, 32) + zlaneRC(c, hh * 128 + 4 * h);
;         const bf16_t* grow = z + zrowU(qrow0, 32) + zlaneRC(c, 6144 + hh * 128 + 4 * h);
; #pragma unroll
;         for (int dt = 0; dt < 4; ++dt)
; #pragma unroll
;             for (int g = 0; g < 4; ++g) {
;                 const int d0 = (dt << 9) | (g << 7);
;                 const u32x2 gv = *(const u32x2*)(grow + d0);
;                 u32x2 o; o.x = pk2(silu_mul(acc[dt][4 * g], bf_lo(gv.x)), silu_mul(acc[dt][4 * g + 1], bf_hi(gv.x)));
;                 o.y = pk2(silu_mul(acc[dt][4 * g + 2], bf_lo(gv.y)), silu_mul(acc[dt][4 * g + 3], bf_hi(gv.y)));
;                 *(u32x2*)(orow + d0) = o;
;             }
;     }
; DI bool attn_next(AttnQueue& q, int lane0, int& qs, int& hd) {
;     for (;;) {
;         if (q.cur >= 8) return false;
;         const int xq = (q.x + q.cur) & 7;
;         const int nqs = NQS / 8 + (xq == 7 ? 1 : 0);
;         unsigned n = 0;
;         if (lane0) n = __hip_atomic_fetch_add(q.heads + 64 * xq, 1u, __ATOMIC_RELAXED, __HIP_MEMORY_SCOPE_AGENT);
;         n = (unsigned)__builtin_amdgcn_readfirstlane((int)n);
;         if (n < (unsigned)(nqs * 16)) { qs = (NQS / 8) * xq + (int)(n >> 4); hd = (int)(n & 15u); return true; }
.LBB0_157:
	v_cmp_gt_u32_e32 vcc, 16, v178
	s_or_b64 s[0:1], s[0:1], vcc
	s_and_saveexec_b64 s[4:5], s[0:1]
	s_xor_b64 s[0:1], exec, s[4:5]
	s_cbranch_execz .LBB0_130
	s_mov_b64 vcc, exec
	s_mov_b64 exec, -1
	v_add_u32_e32 v0, s27, v183
	v_lshlrev_b32_e32 v66, 8, v0
	v_lshlrev_b32_e32 v0, 5, v0
	v_lshlrev_b32_e32 v67, 6, v180
	v_and_b32_e32 v0, 0x1000, v0
	v_and_b32_e32 v68, 0x780, v67
	v_and_b32_e32 v69, 4, v183
	v_or_b32_e32 v67, v68, v69
	v_and_or_b32 v70, v66, s12, v0
	v_or3_b32 v0, v67, v181, v70
	v_lshl_add_u64 v[146:147], v[0:1], 1, s[46:47]
	v_or3_b32 v0, v70, v69, v68
	s_mov_b32 s4, 0x180000
	v_add3_u32 v0, v0, v181, s4
	v_lshl_add_u64 v[148:149], v[0:1], 1, s[46:47]
	s_add_i32 s5, s26, s33
	s_and_b32 s5, s5, 7
	s_lshl_b32 s6, s5, 8
	s_mov_b64 exec, 1
	v_mov_b32_e32 v66, s6
	v_mov_b32_e32 v67, 1
	global_atomic_add v240, v66, v67, s[34:35] sc0
	s_mov_b64 exec, vcc
	global_load_dwordx2 v[192:193], v[148:149], off
	global_load_dwordx2 v[194:195], v[148:149], off offset:256
	global_load_dwordx2 v[196:197], v[148:149], off offset:512
	global_load_dwordx2 v[198:199], v[148:149], off offset:768
	global_load_dwordx2 v[200:201], v[148:149], off offset:1024
	global_load_dwordx2 v[202:203], v[148:149], off offset:1280
	global_load_dwordx2 v[204:205], v[148:149], off offset:1536
	global_load_dwordx2 v[206:207], v[148:149], off offset:1792
	global_load_dwordx2 v[208:209], v[148:149], off offset:2048
	global_load_dwordx2 v[210:211], v[148:149], off offset:2304
	global_load_dwordx2 v[212:213], v[148:149], off offset:2560
	global_load_dwordx2 v[214:215], v[148:149], off offset:2816
	global_load_dwordx2 v[216:217], v[148:149], off offset:3072
	global_load_dwordx2 v[218:219], v[148:149], off offset:3328
	global_load_dwordx2 v[220:221], v[148:149], off offset:3584
	global_load_dwordx2 v[222:223], v[148:149], off offset:3840
	s_waitcnt vmcnt(16)
	s_mov_b64 exec, -1
	v_readfirstlane_b32 s6, v240
	v_mov_b64_e32 v[150:151], v[148:149]
	s_cmp_eq_u32 s5, 7
	s_cselect_b32 s7, s14, 0x400
	s_mov_b32 s101, 0
	s_cmp_lt_u32 s6, s7
	s_cbranch_scc0 .Lpq_dma_B
	s_lshr_b32 s8, s6, 4
	s_sub_i32 s9, 63, s8
	s_cmp_lt_u32 s8, 64
	s_cselect_b32 s8, s9, s8
	s_lshl_b32 s9, s5, 6
	s_add_i32 s8, s8, s9
	s_and_b32 s9, s6, 15
	s_lshl_b32 s10, s9, 12
	s_or_b32 s101, s8, s10
	s_bitset1_b32 s101, 31
	s_lshl_b32 s10, s8, 5
	s_cmp_lt_u32 s8, 0x200
	s_cselect_b32 s10, s10, 0x4000
	s_lshr_b32 s11, s10, 3
	s_and_b32 s78, s11, 0x1fffffe0
	s_lshl_b32 s11, s10, 8
	s_and_b32 s11, s11, 0x8000
	s_lshl_b32 s7, s10, 9
	s_and_b32 s7, s7, 0x4000
	s_or_b32 s11, s11, s7
	s_lshl_b32 s7, s10, 5
	s_and_b32 s7, s7, 0x800
	s_or_b32 s11, s11, s7
	s_lshl_b64 s[6:7], s[78:79], 17
	s_add_u32 s6, s82, s6
	s_addc_u32 s7, s83, s7
	s_lshl_b32 s11, s11, 1
	s_add_u32 s6, s6, s11
	s_addc_u32 s7, s7, 0
	s_lshl_b32 s9, s9, 7
	v_lshl_add_u32 v150, v180, 3, s9
	v_lshlrev_b32_e32 v151, 8, v150
	v_lshlrev_b32_e32 v150, 5, v150
	v_and_b32_e32 v150, 0x1000, v150
	v_and_b32_e32 v151, 0xffff0000, v151
	v_lshlrev_b32_e32 v152, 7, v180
	v_and_b32_e32 v152, 0x780, v152
	v_or3_b32 v150, v150, v151, v152
	v_or_b32_e32 v150, v150, v181
	v_mov_b32_e32 v151, 0
	v_lshl_add_u64 v[150:151], v[150:151], 1, s[6:7]
.Lpq_dma_B:
	s_add_i32 s8, s25, 0x2800
	s_mov_b32 m0, s8
	s_nop 0
	global_load_lds_dwordx4 v[150:151], off
	s_add_i32 m0, s8, 0x200
	s_nop 0
	global_load_lds_dwordx4 v[150:151], off offset:512
	s_add_i32 m0, s8, 0x400
	s_nop 0
	global_load_lds_dwordx4 v[150:151], off offset:1024
	s_add_i32 m0, s8, 0x600
	s_nop 0
	global_load_lds_dwordx4 v[150:151], off offset:1536
	s_add_i32 m0, s8, 0x800
	s_nop 0
	global_load_lds_dwordx4 v[150:151], off offset:2048
	s_add_i32 m0, s8, 0xa00
	s_nop 0
	global_load_lds_dwordx4 v[150:151], off offset:2560
	s_add_i32 m0, s8, 0xc00
	s_nop 0
	global_load_lds_dwordx4 v[150:151], off offset:3072
	s_add_i32 m0, s8, 0xe00
	s_nop 0
	global_load_lds_dwordx4 v[150:151], off offset:3584
	s_mov_b64 exec, vcc
	s_waitcnt vmcnt(23)
	v_lshlrev_b32_e32 v66, 16, v192
	v_and_b32_e32 v67, 0xffff0000, v192
	v_lshlrev_b32_e32 v68, 16, v193
	v_and_b32_e32 v69, 0xffff0000, v193
	v_mul_f32_e32 v70, 0xbfb8aa3b, v66
	v_mul_f32_e32 v71, 0xbfb8aa3b, v67
	v_mul_f32_e32 v72, 0xbfb8aa3b, v68
	v_mul_f32_e32 v73, 0xbfb8aa3b, v69
	v_exp_f32_e32 v70, v70
	v_exp_f32_e32 v71, v71
	v_exp_f32_e32 v72, v72
	v_exp_f32_e32 v73, v73
	v_pk_mul_f32 v[50:51], v[50:51], v[66:67]
	v_pk_mul_f32 v[52:53], v[52:53], v[68:69]
	v_add_f32_e32 v70, 1.0, v70
	v_add_f32_e32 v71, 1.0, v71
	v_add_f32_e32 v72, 1.0, v72
	v_add_f32_e32 v73, 1.0, v73
	v_rcp_f32_e32 v70, v70
	v_rcp_f32_e32 v71, v71
	v_rcp_f32_e32 v72, v72
	v_rcp_f32_e32 v73, v73
	v_pk_mul_f32 v[50:51], v[50:51], v[70:71]
	v_pk_mul_f32 v[52:53], v[52:53], v[72:73]
	v_cvt_pk_bf16_f32 v50, v50, v51
	v_cvt_pk_bf16_f32 v51, v52, v53
	s_waitcnt vmcnt(22)
	v_lshlrev_b32_e32 v74, 16, v194
	v_and_b32_e32 v75, 0xffff0000, v194
	v_lshlrev_b32_e32 v76, 16, v195
	v_and_b32_e32 v77, 0xffff0000, v195
	v_mul_f32_e32 v78, 0xbfb8aa3b, v74
	v_mul_f32_e32 v79, 0xbfb8aa3b, v75
	v_mul_f32_e32 v80, 0xbfb8aa3b, v76
	v_mul_f32_e32 v81, 0xbfb8aa3b, v77
	v_exp_f32_e32 v78, v78
	v_exp_f32_e32 v79, v79
	v_exp_f32_e32 v80, v80
	v_exp_f32_e32 v81, v81
	v_pk_mul_f32 v[54:55], v[54:55], v[74:75]
	v_pk_mul_f32 v[56:57], v[56:57], v[76:77]
	v_add_f32_e32 v78, 1.0, v78
	v_add_f32_e32 v79, 1.0, v79
	v_add_f32_e32 v80, 1.0, v80
	v_add_f32_e32 v81, 1.0, v81
	v_rcp_f32_e32 v78, v78
	v_rcp_f32_e32 v79, v79
	v_rcp_f32_e32 v80, v80
	v_rcp_f32_e32 v81, v81
	v_pk_mul_f32 v[54:55], v[54:55], v[78:79]
	v_pk_mul_f32 v[56:57], v[56:57], v[80:81]
	v_cvt_pk_bf16_f32 v54, v54, v55
	v_cvt_pk_bf16_f32 v55, v56, v57
	s_waitcnt vmcnt(21)
; DI unsigned pk2(float a, float b) { f32x2 v = {a, b}; bf16v2 r = __builtin_convertvector(v, bf16v2); return __builtin_bit_cast(unsigned, r); }
; DI float bf_lo(unsigned u) { return __uint_as_float(u << 16); }
; DI float bf_hi(unsigned u) { return __uint_as_float(u & 0xffff0000u); }
; DI size_t zrowU(int row0, int NT) { return ((size_t)((row0 >> 8) * NT) << 16) + (size_t)((((row0 >> 7) & 1) << 15) | (((row0 >> 5) & 1) << 14) | (((row0 >> 6) & 1) << 11)); }
; DI unsigned zlaneRC(int r5, int col) { return (unsigned)(((col >> 8) << 16) | ((r5 >> 4) << 13) | (((col >> 7) & 1) << 12) | (((col >> 5) & 3) << 9) | (((col >> 3) & 3) << 7) | ((r5 & 15) << 3) | (col & 7)); }
; DI float silu_mul(float o, float g) { return o * g * __builtin_amdgcn_rcpf(1.0f + __builtin_amdgcn_exp2f(g * -1.4426950408889634f)); }
; DI void attnB_item(bf16_t* z, int hh, int qs, LAS bf16_t* vs, int lane) {
;     ...
;     if (!metaq || c < NMETA) {
;         bf16_t* orow = z + zrowU(qrow0, 32) + zlaneRC(c, hh * 128 + 4 * h);
;         const bf16_t* grow = z + zrowU(qrow0, 32) + zlaneRC(c, 6144 + hh * 128 + 4 * h);
; #pragma unroll
;         for (int dt = 0; dt < 4; ++dt)
; #pragma unroll
;             for (int g = 0; g < 4; ++g) {
;                 const int d0 = (dt << 9) | (g << 7);
;                 const u32x2 gv = *(const u32x2*)(grow + d0);
;                 u32x2 o; o.x = pk2(silu_mul(acc[dt][4 * g], bf_lo(gv.x)), silu_mul(acc[dt][4 * g + 1], bf_hi(gv.x)));
;                 o.y = pk2(silu_mul(acc[dt][4 * g + 2], bf_lo(gv.y)), silu_mul(acc[dt][4 * g + 3], bf_hi(gv.y)));
;                 *(u32x2*)(orow + d0) = o;
;             }
;     }
	v_lshlrev_b32_e32 v66, 16, v196
	v_and_b32_e32 v67, 0xffff0000, v196
	v_lshlrev_b32_e32 v68, 16, v197
	v_and_b32_e32 v69, 0xffff0000, v197
	v_mul_f32_e32 v70, 0xbfb8aa3b, v66
	v_mul_f32_e32 v71, 0xbfb8aa3b, v67
	v_mul_f32_e32 v72, 0xbfb8aa3b, v68
	v_mul_f32_e32 v73, 0xbfb8aa3b, v69
	v_exp_f32_e32 v70, v70
	v_exp_f32_e32 v71, v71
	v_exp_f32_e32 v72, v72
	v_exp_f32_e32 v73, v73
	v_pk_mul_f32 v[58:59], v[58:59], v[66:67]
	v_pk_mul_f32 v[60:61], v[60:61], v[68:69]
	v_add_f32_e32 v70, 1.0, v70
	v_add_f32_e32 v71, 1.0, v71
	v_add_f32_e32 v72, 1.0, v72
	v_add_f32_e32 v73, 1.0, v73
	v_rcp_f32_e32 v70, v70
	v_rcp_f32_e32 v71, v71
	v_rcp_f32_e32 v72, v72
	v_rcp_f32_e32 v73, v73
	v_pk_mul_f32 v[58:59], v[58:59], v[70:71]
	v_pk_mul_f32 v[60:61], v[60:61], v[72:73]
	v_cvt_pk_bf16_f32 v58, v58, v59
	v_cvt_pk_bf16_f32 v59, v60, v61
	s_waitcnt vmcnt(20)
	v_lshlrev_b32_e32 v74, 16, v198
	v_and_b32_e32 v75, 0xffff0000, v198
	v_lshlrev_b32_e32 v76, 16, v199
	v_and_b32_e32 v77, 0xffff0000, v199
	v_mul_f32_e32 v78, 0xbfb8aa3b, v74
	v_mul_f32_e32 v79, 0xbfb8aa3b, v75
	v_mul_f32_e32 v80, 0xbfb8aa3b, v76
	v_mul_f32_e32 v81, 0xbfb8aa3b, v77
	v_exp_f32_e32 v78, v78
	v_exp_f32_e32 v79, v79
	v_exp_f32_e32 v80, v80
	v_exp_f32_e32 v81, v81
	v_pk_mul_f32 v[62:63], v[62:63], v[74:75]
	v_pk_mul_f32 v[64:65], v[64:65], v[76:77]
	v_add_f32_e32 v78, 1.0, v78
	v_add_f32_e32 v79, 1.0, v79
	v_add_f32_e32 v80, 1.0, v80
	v_add_f32_e32 v81, 1.0, v81
	v_rcp_f32_e32 v78, v78
	v_rcp_f32_e32 v79, v79
	v_rcp_f32_e32 v80, v80
	v_rcp_f32_e32 v81, v81
	v_pk_mul_f32 v[62:63], v[62:63], v[78:79]
	v_pk_mul_f32 v[64:65], v[64:65], v[80:81]
	v_cvt_pk_bf16_f32 v62, v62, v63
	v_cvt_pk_bf16_f32 v63, v64, v65
	s_waitcnt vmcnt(19)
	v_lshlrev_b32_e32 v66, 16, v200
	v_and_b32_e32 v67, 0xffff0000, v200
	v_lshlrev_b32_e32 v68, 16, v201
	v_and_b32_e32 v69, 0xffff0000, v201
	v_mul_f32_e32 v70, 0xbfb8aa3b, v66
	v_mul_f32_e32 v71, 0xbfb8aa3b, v67
	v_mul_f32_e32 v72, 0xbfb8aa3b, v68
	v_mul_f32_e32 v73, 0xbfb8aa3b, v69
	v_exp_f32_e32 v70, v70
	v_exp_f32_e32 v71, v71
	v_exp_f32_e32 v72, v72
	v_exp_f32_e32 v73, v73
	v_pk_mul_f32 v[34:35], v[34:35], v[66:67]
	v_pk_mul_f32 v[36:37], v[36:37], v[68:69]
	v_add_f32_e32 v70, 1.0, v70
	v_add_f32_e32 v71, 1.0, v71
	v_add_f32_e32 v72, 1.0, v72
	v_add_f32_e32 v73, 1.0, v73
	v_rcp_f32_e32 v70, v70
	v_rcp_f32_e32 v71, v71
	v_rcp_f32_e32 v72, v72
	v_rcp_f32_e32 v73, v73
	v_pk_mul_f32 v[34:35], v[34:35], v[70:71]
	v_pk_mul_f32 v[36:37], v[36:37], v[72:73]
	v_cvt_pk_bf16_f32 v34, v34, v35
	v_cvt_pk_bf16_f32 v35, v36, v37
	s_waitcnt vmcnt(18)
	v_lshlrev_b32_e32 v74, 16, v202
	v_and_b32_e32 v75, 0xffff0000, v202
	v_lshlrev_b32_e32 v76, 16, v203
	v_and_b32_e32 v77, 0xffff0000, v203
	v_mul_f32_e32 v78, 0xbfb8aa3b, v74
	v_mul_f32_e32 v79, 0xbfb8aa3b, v75
	v_mul_f32_e32 v80, 0xbfb8aa3b, v76
	v_mul_f32_e32 v81, 0xbfb8aa3b, v77
	v_exp_f32_e32 v78, v78
	v_exp_f32_e32 v79, v79
	v_exp_f32_e32 v80, v80
	v_exp_f32_e32 v81, v81
	v_pk_mul_f32 v[38:39], v[38:39], v[74:75]
	v_pk_mul_f32 v[40:41], v[40:41], v[76:77]
	v_add_f32_e32 v78, 1.0, v78
	v_add_f32_e32 v79, 1.0, v79
	v_add_f32_e32 v80, 1.0, v80
	v_add_f32_e32 v81, 1.0, v81
	v_rcp_f32_e32 v78, v78
	v_rcp_f32_e32 v79, v79
	v_rcp_f32_e32 v80, v80
	v_rcp_f32_e32 v81, v81
	v_pk_mul_f32 v[38:39], v[38:39], v[78:79]
	v_pk_mul_f32 v[40:41], v[40:41], v[80:81]
	v_cvt_pk_bf16_f32 v38, v38, v39
	v_cvt_pk_bf16_f32 v39, v40, v41
	s_waitcnt vmcnt(17)
	v_lshlrev_b32_e32 v66, 16, v204
	v_and_b32_e32 v67, 0xffff0000, v204
	v_lshlrev_b32_e32 v68, 16, v205
	v_and_b32_e32 v69, 0xffff0000, v205
	v_mul_f32_e32 v70, 0xbfb8aa3b, v66
	v_mul_f32_e32 v71, 0xbfb8aa3b, v67
	v_mul_f32_e32 v72, 0xbfb8aa3b, v68
	v_mul_f32_e32 v73, 0xbfb8aa3b, v69
	v_exp_f32_e32 v70, v70
	v_exp_f32_e32 v71, v71
	v_exp_f32_e32 v72, v72
	v_exp_f32_e32 v73, v73
	v_pk_mul_f32 v[42:43], v[42:43], v[66:67]
	v_pk_mul_f32 v[44:45], v[44:45], v[68:69]
	v_add_f32_e32 v70, 1.0, v70
	v_add_f32_e32 v71, 1.0, v71
	v_add_f32_e32 v72, 1.0, v72
	v_add_f32_e32 v73, 1.0, v73
	v_rcp_f32_e32 v70, v70
	v_rcp_f32_e32 v71, v71
	v_rcp_f32_e32 v72, v72
	v_rcp_f32_e32 v73, v73
	v_pk_mul_f32 v[42:43], v[42:43], v[70:71]
	v_pk_mul_f32 v[44:45], v[44:45], v[72:73]
	v_cvt_pk_bf16_f32 v42, v42, v43
	v_cvt_pk_bf16_f32 v43, v44, v45
	s_waitcnt vmcnt(16)
	v_lshlrev_b32_e32 v74, 16, v206
	v_and_b32_e32 v75, 0xffff0000, v206
	v_lshlrev_b32_e32 v76, 16, v207
	v_and_b32_e32 v77, 0xffff0000, v207
	v_mul_f32_e32 v78, 0xbfb8aa3b, v74
	v_mul_f32_e32 v79, 0xbfb8aa3b, v75
	v_mul_f32_e32 v80, 0xbfb8aa3b, v76
	v_mul_f32_e32 v81, 0xbfb8aa3b, v77
	v_exp_f32_e32 v78, v78
	v_exp_f32_e32 v79, v79
	v_exp_f32_e32 v80, v80
	v_exp_f32_e32 v81, v81
	v_pk_mul_f32 v[46:47], v[46:47], v[74:75]
	v_pk_mul_f32 v[48:49], v[48:49], v[76:77]
	v_add_f32_e32 v78, 1.0, v78
	v_add_f32_e32 v79, 1.0, v79
	v_add_f32_e32 v80, 1.0, v80
	v_add_f32_e32 v81, 1.0, v81
	v_rcp_f32_e32 v78, v78
	v_rcp_f32_e32 v79, v79
	v_rcp_f32_e32 v80, v80
	v_rcp_f32_e32 v81, v81
	v_pk_mul_f32 v[46:47], v[46:47], v[78:79]
	v_pk_mul_f32 v[48:49], v[48:49], v[80:81]
	v_cvt_pk_bf16_f32 v46, v46, v47
	v_cvt_pk_bf16_f32 v47, v48, v49
	s_waitcnt vmcnt(15)
	v_lshlrev_b32_e32 v66, 16, v208
	v_and_b32_e32 v67, 0xffff0000, v208
	v_lshlrev_b32_e32 v68, 16, v209
	v_and_b32_e32 v69, 0xffff0000, v209
	v_mul_f32_e32 v70, 0xbfb8aa3b, v66
	v_mul_f32_e32 v71, 0xbfb8aa3b, v67
	v_mul_f32_e32 v72, 0xbfb8aa3b, v68
	v_mul_f32_e32 v73, 0xbfb8aa3b, v69
	v_exp_f32_e32 v70, v70
	v_exp_f32_e32 v71, v71
	v_exp_f32_e32 v72, v72
	v_exp_f32_e32 v73, v73
	v_pk_mul_f32 v[18:19], v[18:19], v[66:67]
	v_pk_mul_f32 v[20:21], v[20:21], v[68:69]
	v_add_f32_e32 v70, 1.0, v70
	v_add_f32_e32 v71, 1.0, v71
	v_add_f32_e32 v72, 1.0, v72
	v_add_f32_e32 v73, 1.0, v73
	v_rcp_f32_e32 v70, v70
	v_rcp_f32_e32 v71, v71
	v_rcp_f32_e32 v72, v72
	v_rcp_f32_e32 v73, v73
	v_pk_mul_f32 v[18:19], v[18:19], v[70:71]
	v_pk_mul_f32 v[20:21], v[20:21], v[72:73]
	v_cvt_pk_bf16_f32 v18, v18, v19
	v_cvt_pk_bf16_f32 v19, v20, v21
	s_waitcnt vmcnt(14)
; DI unsigned pk2(float a, float b) { f32x2 v = {a, b}; bf16v2 r = __builtin_convertvector(v, bf16v2); return __builtin_bit_cast(unsigned, r); }
; DI float bf_lo(unsigned u) { return __uint_as_float(u << 16); }
; DI float bf_hi(unsigned u) { return __uint_as_float(u & 0xffff0000u); }
; DI size_t zrowU(int row0, int NT) { return ((size_t)((row0 >> 8) * NT) << 16) + (size_t)((((row0 >> 7) & 1) << 15) | (((row0 >> 5) & 1) << 14) | (((row0 >> 6) & 1) << 11)); }
; DI unsigned zlaneRC(int r5, int col) { return (unsigned)(((col >> 8) << 16) | ((r5 >> 4) << 13) | (((col >> 7) & 1) << 12) | (((col >> 5) & 3) << 9) | (((col >> 3) & 3) << 7) | ((r5 & 15) << 3) | (col & 7)); }
; DI float silu_mul(float o, float g) { return o * g * __builtin_amdgcn_rcpf(1.0f + __builtin_amdgcn_exp2f(g * -1.4426950408889634f)); }
; DI void attnB_item(bf16_t* z, int hh, int qs, LAS bf16_t* vs, int lane) {
;     ...
;     if (!metaq || c < NMETA) {
;         bf16_t* orow = z + zrowU(qrow0, 32) + zlaneRC(c, hh * 128 + 4 * h);
;         const bf16_t* grow = z + zrowU(qrow0, 32) + zlaneRC(c, 6144 + hh * 128 + 4 * h);
; #pragma unroll
;         for (int dt = 0; dt < 4; ++dt)
; #pragma unroll
;             for (int g = 0; g < 4; ++g) {
;                 const int d0 = (dt << 9) | (g << 7);
;                 const u32x2 gv = *(const u32x2*)(grow + d0);
;                 u32x2 o; o.x = pk2(silu_mul(acc[dt][4 * g], bf_lo(gv.x)), silu_mul(acc[dt][4 * g + 1], bf_hi(gv.x)));
;                 o.y = pk2(silu_mul(acc[dt][4 * g + 2], bf_lo(gv.y)), silu_mul(acc[dt][4 * g + 3], bf_hi(gv.y)));
;                 *(u32x2*)(orow + d0) = o;
;             }
;     }
	v_lshlrev_b32_e32 v74, 16, v210
	v_and_b32_e32 v75, 0xffff0000, v210
	v_lshlrev_b32_e32 v76, 16, v211
	v_and_b32_e32 v77, 0xffff0000, v211
	v_mul_f32_e32 v78, 0xbfb8aa3b, v74
	v_mul_f32_e32 v79, 0xbfb8aa3b, v75
	v_mul_f32_e32 v80, 0xbfb8aa3b, v76
	v_mul_f32_e32 v81, 0xbfb8aa3b, v77
	v_exp_f32_e32 v78, v78
	v_exp_f32_e32 v79, v79
	v_exp_f32_e32 v80, v80
	v_exp_f32_e32 v81, v81
	v_pk_mul_f32 v[22:23], v[22:23], v[74:75]
	v_pk_mul_f32 v[24:25], v[24:25], v[76:77]
	v_add_f32_e32 v78, 1.0, v78
	v_add_f32_e32 v79, 1.0, v79
	v_add_f32_e32 v80, 1.0, v80
	v_add_f32_e32 v81, 1.0, v81
	v_rcp_f32_e32 v78, v78
	v_rcp_f32_e32 v79, v79
	v_rcp_f32_e32 v80, v80
	v_rcp_f32_e32 v81, v81
	v_pk_mul_f32 v[22:23], v[22:23], v[78:79]
	v_pk_mul_f32 v[24:25], v[24:25], v[80:81]
	v_cvt_pk_bf16_f32 v22, v22, v23
	v_cvt_pk_bf16_f32 v23, v24, v25
	s_waitcnt vmcnt(13)
	v_lshlrev_b32_e32 v66, 16, v212
	v_and_b32_e32 v67, 0xffff0000, v212
	v_lshlrev_b32_e32 v68, 16, v213
	v_and_b32_e32 v69, 0xffff0000, v213
	v_mul_f32_e32 v70, 0xbfb8aa3b, v66
	v_mul_f32_e32 v71, 0xbfb8aa3b, v67
	v_mul_f32_e32 v72, 0xbfb8aa3b, v68
	v_mul_f32_e32 v73, 0xbfb8aa3b, v69
	v_exp_f32_e32 v70, v70
	v_exp_f32_e32 v71, v71
	v_exp_f32_e32 v72, v72
	v_exp_f32_e32 v73, v73
	v_pk_mul_f32 v[26:27], v[26:27], v[66:67]
	v_pk_mul_f32 v[28:29], v[28:29], v[68:69]
	v_add_f32_e32 v70, 1.0, v70
	v_add_f32_e32 v71, 1.0, v71
	v_add_f32_e32 v72, 1.0, v72
	v_add_f32_e32 v73, 1.0, v73
	v_rcp_f32_e32 v70, v70
	v_rcp_f32_e32 v71, v71
	v_rcp_f32_e32 v72, v72
	v_rcp_f32_e32 v73, v73
	v_pk_mul_f32 v[26:27], v[26:27], v[70:71]
	v_pk_mul_f32 v[28:29], v[28:29], v[72:73]
	v_cvt_pk_bf16_f32 v26, v26, v27
	v_cvt_pk_bf16_f32 v27, v28, v29
	s_waitcnt vmcnt(12)
	v_lshlrev_b32_e32 v74, 16, v214
	v_and_b32_e32 v75, 0xffff0000, v214
	v_lshlrev_b32_e32 v76, 16, v215
	v_and_b32_e32 v77, 0xffff0000, v215
	v_mul_f32_e32 v78, 0xbfb8aa3b, v74
	v_mul_f32_e32 v79, 0xbfb8aa3b, v75
	v_mul_f32_e32 v80, 0xbfb8aa3b, v76
	v_mul_f32_e32 v81, 0xbfb8aa3b, v77
	v_exp_f32_e32 v78, v78
	v_exp_f32_e32 v79, v79
	v_exp_f32_e32 v80, v80
	v_exp_f32_e32 v81, v81
	v_pk_mul_f32 v[30:31], v[30:31], v[74:75]
	v_pk_mul_f32 v[32:33], v[32:33], v[76:77]
	v_add_f32_e32 v78, 1.0, v78
	v_add_f32_e32 v79, 1.0, v79
	v_add_f32_e32 v80, 1.0, v80
	v_add_f32_e32 v81, 1.0, v81
	v_rcp_f32_e32 v78, v78
	v_rcp_f32_e32 v79, v79
	v_rcp_f32_e32 v80, v80
	v_rcp_f32_e32 v81, v81
	v_pk_mul_f32 v[30:31], v[30:31], v[78:79]
	v_pk_mul_f32 v[32:33], v[32:33], v[80:81]
	v_cvt_pk_bf16_f32 v30, v30, v31
	v_cvt_pk_bf16_f32 v31, v32, v33
	s_waitcnt vmcnt(11)
	v_lshlrev_b32_e32 v66, 16, v216
	v_and_b32_e32 v67, 0xffff0000, v216
	v_lshlrev_b32_e32 v68, 16, v217
	v_and_b32_e32 v69, 0xffff0000, v217
	v_mul_f32_e32 v70, 0xbfb8aa3b, v66
	v_mul_f32_e32 v71, 0xbfb8aa3b, v67
	v_mul_f32_e32 v72, 0xbfb8aa3b, v68
	v_mul_f32_e32 v73, 0xbfb8aa3b, v69
	v_exp_f32_e32 v70, v70
	v_exp_f32_e32 v71, v71
	v_exp_f32_e32 v72, v72
	v_exp_f32_e32 v73, v73
	v_pk_mul_f32 v[2:3], v[2:3], v[66:67]
	v_pk_mul_f32 v[4:5], v[4:5], v[68:69]
	v_add_f32_e32 v70, 1.0, v70
	v_add_f32_e32 v71, 1.0, v71
	v_add_f32_e32 v72, 1.0, v72
	v_add_f32_e32 v73, 1.0, v73
	v_rcp_f32_e32 v70, v70
	v_rcp_f32_e32 v71, v71
	v_rcp_f32_e32 v72, v72
	v_rcp_f32_e32 v73, v73
	v_pk_mul_f32 v[2:3], v[2:3], v[70:71]
	v_pk_mul_f32 v[4:5], v[4:5], v[72:73]
	v_cvt_pk_bf16_f32 v2, v2, v3
	v_cvt_pk_bf16_f32 v3, v4, v5
	s_waitcnt vmcnt(10)
	v_lshlrev_b32_e32 v74, 16, v218
	v_and_b32_e32 v75, 0xffff0000, v218
	v_lshlrev_b32_e32 v76, 16, v219
	v_and_b32_e32 v77, 0xffff0000, v219
	v_mul_f32_e32 v78, 0xbfb8aa3b, v74
	v_mul_f32_e32 v79, 0xbfb8aa3b, v75
	v_mul_f32_e32 v80, 0xbfb8aa3b, v76
	v_mul_f32_e32 v81, 0xbfb8aa3b, v77
	v_exp_f32_e32 v78, v78
	v_exp_f32_e32 v79, v79
	v_exp_f32_e32 v80, v80
	v_exp_f32_e32 v81, v81
	v_pk_mul_f32 v[6:7], v[6:7], v[74:75]
	v_pk_mul_f32 v[8:9], v[8:9], v[76:77]
	v_add_f32_e32 v78, 1.0, v78
	v_add_f32_e32 v79, 1.0, v79
	v_add_f32_e32 v80, 1.0, v80
	v_add_f32_e32 v81, 1.0, v81
	v_rcp_f32_e32 v78, v78
	v_rcp_f32_e32 v79, v79
	v_rcp_f32_e32 v80, v80
	v_rcp_f32_e32 v81, v81
	v_pk_mul_f32 v[6:7], v[6:7], v[78:79]
	v_pk_mul_f32 v[8:9], v[8:9], v[80:81]
	v_cvt_pk_bf16_f32 v6, v6, v7
	v_cvt_pk_bf16_f32 v7, v8, v9
	s_waitcnt vmcnt(9)
	v_lshlrev_b32_e32 v66, 16, v220
	v_and_b32_e32 v67, 0xffff0000, v220
	v_lshlrev_b32_e32 v68, 16, v221
	v_and_b32_e32 v69, 0xffff0000, v221
	v_mul_f32_e32 v70, 0xbfb8aa3b, v66
	v_mul_f32_e32 v71, 0xbfb8aa3b, v67
	v_mul_f32_e32 v72, 0xbfb8aa3b, v68
	v_mul_f32_e32 v73, 0xbfb8aa3b, v69
	v_exp_f32_e32 v70, v70
	v_exp_f32_e32 v71, v71
	v_exp_f32_e32 v72, v72
	v_exp_f32_e32 v73, v73
	v_pk_mul_f32 v[10:11], v[10:11], v[66:67]
	v_pk_mul_f32 v[12:13], v[12:13], v[68:69]
	v_add_f32_e32 v70, 1.0, v70
	v_add_f32_e32 v71, 1.0, v71
	v_add_f32_e32 v72, 1.0, v72
	v_add_f32_e32 v73, 1.0, v73
	v_rcp_f32_e32 v70, v70
	v_rcp_f32_e32 v71, v71
	v_rcp_f32_e32 v72, v72
	v_rcp_f32_e32 v73, v73
	v_pk_mul_f32 v[10:11], v[10:11], v[70:71]
	v_pk_mul_f32 v[12:13], v[12:13], v[72:73]
	v_cvt_pk_bf16_f32 v10, v10, v11
	v_cvt_pk_bf16_f32 v11, v12, v13
	s_waitcnt vmcnt(8)
	v_lshlrev_b32_e32 v74, 16, v222
	v_and_b32_e32 v75, 0xffff0000, v222
	v_lshlrev_b32_e32 v76, 16, v223
	v_and_b32_e32 v77, 0xffff0000, v223
	v_mul_f32_e32 v78, 0xbfb8aa3b, v74
	v_mul_f32_e32 v79, 0xbfb8aa3b, v75
	v_mul_f32_e32 v80, 0xbfb8aa3b, v76
	v_mul_f32_e32 v81, 0xbfb8aa3b, v77
	v_exp_f32_e32 v78, v78
	v_exp_f32_e32 v79, v79
	v_exp_f32_e32 v80, v80
	v_exp_f32_e32 v81, v81
	v_pk_mul_f32 v[14:15], v[14:15], v[74:75]
	v_pk_mul_f32 v[16:17], v[16:17], v[76:77]
	v_add_f32_e32 v78, 1.0, v78
	v_add_f32_e32 v79, 1.0, v79
	v_add_f32_e32 v80, 1.0, v80
	v_add_f32_e32 v81, 1.0, v81
	v_rcp_f32_e32 v78, v78
	v_rcp_f32_e32 v79, v79
	v_rcp_f32_e32 v80, v80
	v_rcp_f32_e32 v81, v81
	v_pk_mul_f32 v[14:15], v[14:15], v[78:79]
	v_pk_mul_f32 v[16:17], v[16:17], v[80:81]
	v_cvt_pk_bf16_f32 v14, v14, v15
	v_cvt_pk_bf16_f32 v15, v16, v17
	global_store_dwordx2 v[146:147], v[50:51], off
	global_store_dwordx2 v[146:147], v[54:55], off offset:256
	global_store_dwordx2 v[146:147], v[58:59], off offset:512
	global_store_dwordx2 v[146:147], v[62:63], off offset:768
	global_store_dwordx2 v[146:147], v[34:35], off offset:1024
	global_store_dwordx2 v[146:147], v[38:39], off offset:1280
	global_store_dwordx2 v[146:147], v[42:43], off offset:1536
	global_store_dwordx2 v[146:147], v[46:47], off offset:1792
	global_store_dwordx2 v[146:147], v[18:19], off offset:2048
	global_store_dwordx2 v[146:147], v[22:23], off offset:2304
	global_store_dwordx2 v[146:147], v[26:27], off offset:2560
	global_store_dwordx2 v[146:147], v[30:31], off offset:2816
	global_store_dwordx2 v[146:147], v[2:3], off offset:3072
	global_store_dwordx2 v[146:147], v[6:7], off offset:3328
	global_store_dwordx2 v[146:147], v[10:11], off offset:3584
	global_store_dwordx2 v[146:147], v[14:15], off offset:3840
	s_branch .LBB0_130
